# v44: LN1 and fixup stores write-through (sc1) so their barriers skip the L2 writeback
# baseline (speedup 1.0000x reference)
; __device__ __forceinline__ f32x4 unpk4(u32x2 w) { f32x4 r; r.x = bflo(w.x); r.y = bfhi(w.x); r.z = bflo(w.y); r.w = bfhi(w.y); return r; }
; template <int WHICH, int NRW>
; __device__ __forceinline__ void ln_rows(const Params& p, const int row0, const int lane, const f32x4 (&gv)[4], const f32x4 (&bv)[4]) {
;   bf16_t* X1b = (bf16_t*)(p.ws + OFF_X1B);
;   f32x4 v[NRW][4];
; #pragma unroll
;   for (int h = 0; h < NRW; ++h) {
;     const int row = row0 + h;
;     if (row < MP) {
;       const bf16_t* xr = (const bf16_t*)(p.ws + (WHICH == 1 ? OFF_PRE1 : OFF_PRE2)) + (size_t)row * DM;
; #pragma unroll
;       for (int j = 0; j < 4; ++j) v[h][j] = unpk4(*(const u32x2*)(xr + j * 256 + lane * 4));
;     } else {
;       const float* SL = (const float*)(p.ws + (WHICH == 1 ? OFF_SLAB_WO : OFF_SLAB_DN)) + (size_t)(row - MP) * DM;
;       constexpr int NS = (WHICH == 1) ? 8 : 11;
; #pragma unroll
;       for (int j = 0; j < 4; ++j) {
;         f32x4 a;
;         if (WHICH == 1) a = *(const f32x4*)(p.in[1] + (size_t)(row - MP) * DM + j * 256 + lane * 4) * ALPHA_F;
;         else a = unpk4(*(const u32x2*)(X1b + (size_t)row * DM + j * 256 + lane * 4)) * ALPHA_F;
; #pragma unroll
;         for (int q = 0; q < NS; ++q) a += *(const f32x4*)(SL + (size_t)q * MS * DM + j * 256 + lane * 4);
;         v[h][j] = a;
;       }
;     }
;   }
;   float s[NRW], s2[NRW];
; #pragma unroll
;   for (int h = 0; h < NRW; ++h) { s[h] = 0.f;
; #pragma unroll
;     for (int j = 0; j < 4; ++j) s[h] += (v[h][j].x + v[h][j].y) + (v[h][j].z + v[h][j].w); }
; #pragma unroll
;   for (int o = 1; o < 64; o <<= 1) {
; #pragma unroll
;     for (int h = 0; h < NRW; ++h) s[h] += __shfl_xor(s[h], o);
;   }
; #pragma unroll
;   for (int h = 0; h < NRW; ++h) { const float mean = s[h] * (1.f / DM); s2[h] = 0.f;
; #pragma unroll
;     for (int j = 0; j < 4; ++j) { v[h][j] = v[h][j] - mean; s2[h] += (v[h][j].x * v[h][j].x + v[h][j].y * v[h][j].y) + (v[h][j].z * v[h][j].z + v[h][j].w * v[h][j].w); } }
; #pragma unroll
;   for (int o = 1; o < 64; o <<= 1) {
; #pragma unroll
;     for (int h = 0; h < NRW; ++h) s2[h] += __shfl_xor(s2[h], o);
;   }
.LBB0_891:
	v_ashrrev_i32_e32 v39, 31, v38
	v_lshlrev_b64 v[64:65], 11, v[38:39]
	v_lshl_add_u64 v[42:43], v[34:35], 0, v[64:65]
	global_load_dwordx2 v[44:45], v[42:43], off offset:1024
	global_load_dwordx2 v[46:47], v[42:43], off offset:1536
	global_load_dwordx2 v[48:49], v[42:43], off
	global_load_dwordx2 v[50:51], v[42:43], off offset:512
	v_add_u32_e32 v42, 1, v38
	v_ashrrev_i32_e32 v43, 31, v42
	v_lshlrev_b64 v[42:43], 11, v[42:43]
	v_lshl_add_u64 v[52:53], v[34:35], 0, v[42:43]
	global_load_dwordx2 v[54:55], v[52:53], off offset:1024
	global_load_dwordx2 v[70:71], v[52:53], off offset:1536
	global_load_dwordx2 v[72:73], v[52:53], off
	global_load_dwordx2 v[84:85], v[52:53], off offset:512
	v_lshl_add_u64 v[64:65], v[36:37], 0, v[64:65]
	v_lshl_add_u64 v[42:43], v[36:37], 0, v[42:43]
	v_add_u32_e32 v83, s66, v83
	v_add_u32_e32 v38, s3, v38
	s_waitcnt vmcnt(7)
	v_lshlrev_b32_e32 v66, 16, v44
	v_and_b32_e32 v67, 0xffff0000, v44
	s_waitcnt vmcnt(5)
	v_lshlrev_b32_e32 v77, 16, v49
	v_lshlrev_b32_e32 v76, 16, v48
	v_and_b32_e32 v87, 0xffff0000, v49
	v_and_b32_e32 v86, 0xffff0000, v48
	s_waitcnt vmcnt(4)
	v_lshlrev_b32_e32 v75, 16, v51
	v_lshlrev_b32_e32 v74, 16, v50
	v_and_b32_e32 v89, 0xffff0000, v51
	v_and_b32_e32 v88, 0xffff0000, v50
	v_pk_add_f32 v[90:91], v[76:77], v[86:87]
	v_pk_add_f32 v[92:93], v[74:75], v[88:89]
	v_lshlrev_b32_e32 v68, 16, v45
	v_and_b32_e32 v69, 0xffff0000, v45
	v_and_b32_e32 v59, 0xffff0000, v46
	v_add_f32_e32 v39, v90, v91
	v_pk_add_f32 v[90:91], v[92:93], v[92:93] op_sel:[0,1] op_sel_hi:[1,0]
	v_lshlrev_b32_e32 v63, 16, v46
	v_lshlrev_b32_e32 v61, 16, v47
	v_and_b32_e32 v57, 0xffff0000, v47
	s_waitcnt vmcnt(2)
	v_lshlrev_b32_e32 v51, 16, v70
	v_and_b32_e32 v47, 0xffff0000, v70
	v_lshlrev_b32_e32 v49, 16, v71
	v_and_b32_e32 v45, 0xffff0000, v71
	v_add_f32_e32 v60, v66, v67
	v_add_f32_e32 v56, v68, v69
	s_waitcnt vmcnt(1)
	v_lshlrev_b32_e32 v71, 16, v73
	v_lshlrev_b32_e32 v70, 16, v72
	v_and_b32_e32 v95, 0xffff0000, v73
	v_and_b32_e32 v94, 0xffff0000, v72
	v_add_f32_e32 v62, 0, v39
	v_mov_b32_e32 v91, v59
	v_pk_add_f32 v[92:93], v[60:61], v[56:57]
	v_pk_add_f32 v[96:97], v[70:71], v[94:95]
	v_pk_add_f32 v[90:91], v[62:63], v[90:91]
	s_waitcnt vmcnt(0)
	v_lshlrev_b32_e32 v73, 16, v85
	v_lshlrev_b32_e32 v72, 16, v84
	v_and_b32_e32 v85, 0xffff0000, v85
	v_and_b32_e32 v84, 0xffff0000, v84
	v_add_f32_e32 v39, v96, v97
	v_pk_add_f32 v[90:91], v[90:91], v[92:93]
	v_pk_add_f32 v[98:99], v[72:73], v[84:85]
	v_add_f32_e32 v50, 0, v39
	v_add_f32_e32 v39, v90, v91
	v_lshlrev_b32_e32 v52, 16, v54
	v_and_b32_e32 v53, 0xffff0000, v54
	v_lshlrev_b32_e32 v54, 16, v55
	v_and_b32_e32 v55, 0xffff0000, v55
	v_pk_add_f32 v[96:97], v[98:99], v[98:99] op_sel:[0,1] op_sel_hi:[1,0]
	ds_bpermute_b32 v46, v41, v39
	v_add_f32_e32 v48, v52, v53
	v_add_f32_e32 v44, v54, v55
	v_mov_b32_e32 v97, v47
	v_pk_add_f32 v[98:99], v[48:49], v[44:45]
	v_pk_add_f32 v[92:93], v[50:51], v[96:97]
	s_waitcnt lgkmcnt(0)
	v_add_f32_e32 v39, v39, v46
	v_pk_add_f32 v[90:91], v[92:93], v[98:99]
	ds_bpermute_b32 v46, v78, v39
	v_add_f32_e32 v44, v90, v91
	ds_bpermute_b32 v48, v41, v44
	s_waitcnt lgkmcnt(1)
	v_add_f32_e32 v39, v39, v46
	ds_bpermute_b32 v46, v79, v39
	s_waitcnt lgkmcnt(1)
	v_add_f32_e32 v44, v44, v48
	ds_bpermute_b32 v48, v78, v44
	s_waitcnt lgkmcnt(1)
	v_add_f32_e32 v39, v39, v46
	ds_bpermute_b32 v46, v80, v39
	s_waitcnt lgkmcnt(1)
	v_add_f32_e32 v44, v44, v48
	ds_bpermute_b32 v48, v79, v44
	s_waitcnt lgkmcnt(1)
	v_add_f32_e32 v39, v39, v46
	ds_bpermute_b32 v46, v81, v39
	s_waitcnt lgkmcnt(1)
	v_add_f32_e32 v44, v44, v48
	ds_bpermute_b32 v48, v80, v44
	s_waitcnt lgkmcnt(1)
	v_add_f32_e32 v39, v39, v46
	ds_bpermute_b32 v46, v82, v39
	s_waitcnt lgkmcnt(1)
	v_add_f32_e32 v44, v44, v48
	ds_bpermute_b32 v48, v81, v44
	s_waitcnt lgkmcnt(1)
	v_add_f32_e32 v39, v39, v46
	v_fmac_f32_e32 v86, 0xba800000, v39
	s_waitcnt lgkmcnt(0)
	v_add_f32_e32 v44, v44, v48
	ds_bpermute_b32 v48, v82, v44
	v_fmac_f32_e32 v87, 0xba800000, v39
	v_fmac_f32_e32 v77, 0xba800000, v39
	v_fmac_f32_e32 v88, 0xba800000, v39
	v_fmac_f32_e32 v89, 0xba800000, v39
	v_fmac_f32_e32 v75, 0xba800000, v39
	v_fmac_f32_e32 v76, 0xba800000, v39
	v_fmac_f32_e32 v74, 0xba800000, v39
	v_mov_b32_e32 v90, v77
	v_mov_b32_e32 v91, v87
	v_mov_b32_e32 v77, v86
	v_mov_b32_e32 v86, v75
	v_mov_b32_e32 v87, v89
	v_mov_b32_e32 v75, v88
	v_pk_mul_f32 v[88:89], v[90:91], v[90:91]
	v_pk_mul_f32 v[92:93], v[76:77], v[76:77]
	v_pk_mul_f32 v[96:97], v[86:87], v[86:87]
	v_pk_mul_f32 v[98:99], v[74:75], v[74:75]
	v_fmac_f32_e32 v66, 0xba800000, v39
	v_fmac_f32_e32 v68, 0xba800000, v39
	v_pk_mov_b32 v[104:105], v[92:93], v[88:89] op_sel:[1,0]
	v_mov_b32_e32 v93, v89
	v_pk_mov_b32 v[88:89], v[98:99], v[96:97] op_sel:[1,0]
	v_mov_b32_e32 v99, v97
	s_waitcnt lgkmcnt(0)
; __device__ __forceinline__ u32x2 pk4(f32x4 v) { u32x2 r; r.x = pk2(v.x, v.y); r.y = pk2(v.z, v.w); return r; }
; template <int WHICH, int NRW>
; __device__ __forceinline__ void ln_rows(const Params& p, const int row0, const int lane, const f32x4 (&gv)[4], const f32x4 (&bv)[4]) {
;     ...
;   for (int h = 0; h < NRW; ++h) { const float mean = s[h] * (1.f / DM); s2[h] = 0.f;
; #pragma unroll
;     for (int j = 0; j < 4; ++j) { v[h][j] = v[h][j] - mean; s2[h] += (v[h][j].x * v[h][j].x + v[h][j].y * v[h][j].y) + (v[h][j].z * v[h][j].z + v[h][j].w * v[h][j].w); } }
; #pragma unroll
;   for (int o = 1; o < 64; o <<= 1) {
; #pragma unroll
;     for (int h = 0; h < NRW; ++h) s2[h] += __shfl_xor(s2[h], o);
;   }
; #pragma unroll
;   for (int h = 0; h < NRW; ++h) {
;     const int row = row0 + h;
;     const float rstd = rsqrtf(s2[h] * (1.f / DM) + LN_EPS_F);
; #pragma unroll
;     for (int j = 0; j < 4; ++j) {
;       const f32x4 o = v[h][j] * rstd * gv[j] + bv[j];
;       if (WHICH == 1) *(u32x2*)(X1b + (size_t)row * DM + j * 256 + lane * 4) = pk4(o);
;       else *(f32x4*)(p.out + (size_t)row * DM + j * 256 + lane * 4) = o;
;     }
;   }
	v_add_f32_e32 v48, v44, v48
	v_fmac_f32_e32 v67, 0xba800000, v39
	v_fmac_f32_e32 v69, 0xba800000, v39
	v_mul_f32_e32 v44, v66, v66
	v_mul_f32_e32 v46, v68, v68
	v_pk_add_f32 v[92:93], v[104:105], v[92:93]
	v_pk_add_f32 v[88:89], v[88:89], v[98:99]
	v_fmac_f32_e32 v57, 0xba800000, v39
	v_fmac_f32_e32 v61, 0xba800000, v39
	v_fmac_f32_e32 v59, 0xba800000, v39
	v_pk_fma_f32 v[100:101], v[66:67], v[66:67], v[44:45] op_sel_hi:[1,1,0]
	v_pk_fma_f32 v[102:103], v[68:69], v[68:69], v[46:47] op_sel_hi:[1,1,0]
	v_pk_add_f32 v[92:93], v[92:93], v[92:93] op_sel_hi:[0,1]
	v_pk_add_f32 v[88:89], v[88:89], v[88:89] op_sel_hi:[0,1]
	v_fmac_f32_e32 v63, 0xba800000, v39
	v_mul_f32_e32 v100, v63, v63
	v_mul_f32_e32 v102, v59, v59
	v_mul_f32_e32 v92, v61, v61
	v_mul_f32_e32 v88, v57, v57
	v_fmac_f32_e32 v94, 0xba800000, v48
	v_fmac_f32_e32 v95, 0xba800000, v48
	v_fmac_f32_e32 v71, 0xba800000, v48
	v_pk_add_f32 v[96:97], v[100:101], v[102:103]
	v_pk_add_f32 v[88:89], v[92:93], v[88:89]
	v_fmac_f32_e32 v70, 0xba800000, v48
	v_mov_b32_e32 v92, v71
	v_mov_b32_e32 v93, v95
	v_mov_b32_e32 v71, v94
	v_pk_add_f32 v[88:89], v[96:97], v[88:89]
	v_pk_mul_f32 v[96:97], v[92:93], v[92:93]
	v_pk_mul_f32 v[94:95], v[70:71], v[70:71]
	v_fmac_f32_e32 v84, 0xba800000, v48
	v_fmac_f32_e32 v85, 0xba800000, v48
	v_fmac_f32_e32 v73, 0xba800000, v48
	v_pk_mov_b32 v[98:99], v[94:95], v[96:97] op_sel:[1,0]
	v_mov_b32_e32 v95, v97
	v_fmac_f32_e32 v72, 0xba800000, v48
	v_mov_b32_e32 v96, v73
	v_mov_b32_e32 v97, v85
	v_mov_b32_e32 v73, v84
	v_pk_add_f32 v[94:95], v[98:99], v[94:95]
	v_pk_mul_f32 v[98:99], v[96:97], v[96:97]
	v_pk_mul_f32 v[84:85], v[72:73], v[72:73]
	v_fmac_f32_e32 v52, 0xba800000, v48
	v_pk_mov_b32 v[100:101], v[84:85], v[98:99] op_sel:[1,0]
	v_mov_b32_e32 v85, v99
	v_fmac_f32_e32 v53, 0xba800000, v48
	v_fmac_f32_e32 v54, 0xba800000, v48
	v_mul_f32_e32 v44, v52, v52
	v_pk_add_f32 v[84:85], v[100:101], v[84:85]
	v_fmac_f32_e32 v55, 0xba800000, v48
	v_pk_fma_f32 v[98:99], v[52:53], v[52:53], v[44:45] op_sel_hi:[1,1,0]
	v_mul_f32_e32 v44, v54, v54
	v_pk_add_f32 v[94:95], v[94:95], v[94:95] op_sel_hi:[0,1]
	v_pk_add_f32 v[84:85], v[84:85], v[84:85] op_sel_hi:[0,1]
	v_pk_fma_f32 v[100:101], v[54:55], v[54:55], v[44:45] op_sel_hi:[1,1,0]
	v_fmac_f32_e32 v45, 0xba800000, v48
	v_fmac_f32_e32 v49, 0xba800000, v48
	v_fmac_f32_e32 v47, 0xba800000, v48
	v_fmac_f32_e32 v51, 0xba800000, v48
	v_mul_f32_e32 v98, v51, v51
	v_mul_f32_e32 v100, v47, v47
	v_mul_f32_e32 v94, v49, v49
	v_mul_f32_e32 v84, v45, v45
	v_pk_add_f32 v[98:99], v[98:99], v[100:101]
	v_pk_add_f32 v[84:85], v[94:95], v[84:85]
	v_mov_b32_e32 v95, v88
	v_pk_add_f32 v[84:85], v[98:99], v[84:85]
	v_mov_b32_e32 v58, v63
	v_mov_b32_e32 v94, v84
	v_mov_b32_e32 v88, v85
	v_pk_add_f32 v[84:85], v[94:95], v[88:89]
	ds_bpermute_b32 v89, v41, v85
	ds_bpermute_b32 v88, v41, v84
	v_mov_b32_e32 v56, v61
	v_mov_b32_e32 v46, v51
	s_waitcnt lgkmcnt(0)
	v_pk_add_f32 v[84:85], v[84:85], v[88:89]
	ds_bpermute_b32 v89, v78, v85
	ds_bpermute_b32 v88, v78, v84
	s_waitcnt lgkmcnt(0)
	v_pk_add_f32 v[84:85], v[84:85], v[88:89]
	ds_bpermute_b32 v89, v79, v85
	ds_bpermute_b32 v88, v79, v84
	s_waitcnt lgkmcnt(0)
	v_pk_add_f32 v[84:85], v[84:85], v[88:89]
	ds_bpermute_b32 v89, v80, v85
	ds_bpermute_b32 v88, v80, v84
	s_waitcnt lgkmcnt(0)
	v_pk_add_f32 v[84:85], v[84:85], v[88:89]
	ds_bpermute_b32 v89, v81, v85
	ds_bpermute_b32 v88, v81, v84
	s_waitcnt lgkmcnt(0)
	v_pk_add_f32 v[84:85], v[84:85], v[88:89]
	ds_bpermute_b32 v89, v82, v85
	ds_bpermute_b32 v88, v82, v84
	s_waitcnt lgkmcnt(0)
	v_pk_add_f32 v[84:85], v[84:85], v[88:89]
	s_nop 0
	v_pk_fma_f32 v[84:85], v[84:85], s[8:9], v[40:41] op_sel_hi:[1,0,0]
	s_nop 0
	v_mul_f32_e32 v39, 0x4b800000, v85
	v_cmp_gt_f32_e32 vcc, s9, v85
	s_nop 1
	v_cndmask_b32_e32 v39, v85, v39, vcc
	v_rsq_f32_e32 v39, v39
	s_nop 0
	v_mul_f32_e32 v44, 0x45800000, v39
	v_cndmask_b32_e32 v44, v39, v44, vcc
	v_mul_f32_e32 v39, 0x4b800000, v84
	v_cmp_gt_f32_e32 vcc, s9, v84
	v_pk_mul_f32 v[76:77], v[76:77], v[44:45] op_sel_hi:[1,0]
	v_pk_mul_f32 v[88:89], v[90:91], v[44:45] op_sel_hi:[1,0]
	v_cndmask_b32_e32 v39, v84, v39, vcc
	v_rsq_f32_e32 v39, v39
	v_pk_fma_f32 v[88:89], v[4:5], v[88:89], v[8:9]
	v_pk_fma_f32 v[76:77], v[2:3], v[76:77], v[6:7]
	v_pk_mul_f32 v[58:59], v[58:59], v[44:45] op_sel_hi:[1,0]
	v_cvt_pk_bf16_f32 v76, v76, v77
	v_cvt_pk_bf16_f32 v77, v88, v89
	v_pk_mul_f32 v[56:57], v[56:57], v[44:45] op_sel_hi:[1,0]
	global_store_dwordx2 v[64:65], v[76:77], off sc1
	v_pk_mul_f32 v[74:75], v[74:75], v[44:45] op_sel_hi:[1,0]
	v_pk_mul_f32 v[76:77], v[86:87], v[44:45] op_sel_hi:[1,0]
	v_pk_mul_f32 v[66:67], v[66:67], v[44:45] op_sel_hi:[1,0]
	v_pk_mul_f32 v[68:69], v[68:69], v[44:45] op_sel_hi:[1,0]
	v_pk_fma_f32 v[56:57], v[28:29], v[56:57], v[32:33]
	v_pk_fma_f32 v[58:59], v[26:27], v[58:59], v[30:31]
	v_mul_f32_e32 v44, 0x45800000, v39
	v_cvt_pk_bf16_f32 v58, v58, v59
	v_cvt_pk_bf16_f32 v59, v56, v57
	v_cndmask_b32_e32 v48, v39, v44, vcc
	global_store_dwordx2 v[64:65], v[58:59], off offset:1536 sc1
	v_pk_mul_f32 v[56:57], v[70:71], v[48:49] op_sel_hi:[1,0]
	v_pk_mul_f32 v[58:59], v[92:93], v[48:49] op_sel_hi:[1,0]
	v_pk_fma_f32 v[56:57], v[2:3], v[56:57], v[6:7]
	v_pk_fma_f32 v[58:59], v[4:5], v[58:59], v[8:9]
	v_cvt_pk_bf16_f32 v56, v56, v57
	v_cvt_pk_bf16_f32 v57, v58, v59
	v_mov_b32_e32 v44, v49
	global_store_dwordx2 v[42:43], v[56:57], off sc1
	v_pk_mul_f32 v[56:57], v[72:73], v[48:49] op_sel_hi:[1,0]
	v_pk_mul_f32 v[58:59], v[96:97], v[48:49] op_sel_hi:[1,0]
	v_pk_mul_f32 v[52:53], v[52:53], v[48:49] op_sel_hi:[1,0]
	v_pk_mul_f32 v[54:55], v[54:55], v[48:49] op_sel_hi:[1,0]
	v_pk_mul_f32 v[46:47], v[46:47], v[48:49] op_sel_hi:[1,0]
	v_pk_mul_f32 v[44:45], v[44:45], v[48:49] op_sel_hi:[1,0]
	v_pk_fma_f32 v[76:77], v[12:13], v[76:77], v[16:17]
	v_pk_fma_f32 v[74:75], v[10:11], v[74:75], v[14:15]
	v_pk_fma_f32 v[68:69], v[20:21], v[68:69], v[24:25]
	v_pk_fma_f32 v[66:67], v[18:19], v[66:67], v[22:23]
	v_pk_fma_f32 v[58:59], v[12:13], v[58:59], v[16:17]
	v_pk_fma_f32 v[56:57], v[10:11], v[56:57], v[14:15]
	v_pk_fma_f32 v[54:55], v[20:21], v[54:55], v[24:25]
	v_pk_fma_f32 v[52:53], v[18:19], v[52:53], v[22:23]
	v_pk_fma_f32 v[44:45], v[28:29], v[44:45], v[32:33]
	v_pk_fma_f32 v[46:47], v[26:27], v[46:47], v[30:31]
	v_cmp_lt_i32_e32 vcc, s10, v83
	v_cvt_pk_bf16_f32 v74, v74, v75
	v_cvt_pk_bf16_f32 v75, v76, v77
	v_cvt_pk_bf16_f32 v66, v66, v67
	v_cvt_pk_bf16_f32 v67, v68, v69
	v_cvt_pk_bf16_f32 v56, v56, v57
	v_cvt_pk_bf16_f32 v57, v58, v59
	v_cvt_pk_bf16_f32 v52, v52, v53
	v_cvt_pk_bf16_f32 v53, v54, v55
	v_cvt_pk_bf16_f32 v46, v46, v47
	v_cvt_pk_bf16_f32 v47, v44, v45
	s_or_b64 s[6:7], vcc, s[6:7]
	global_store_dwordx2 v[64:65], v[74:75], off offset:512 sc1
	global_store_dwordx2 v[64:65], v[66:67], off offset:1024 sc1
	global_store_dwordx2 v[42:43], v[56:57], off offset:512 sc1
	global_store_dwordx2 v[42:43], v[52:53], off offset:1024 sc1
	global_store_dwordx2 v[42:43], v[46:47], off offset:1536 sc1
	s_andn2_b64 exec, exec, s[6:7]
	s_cbranch_execnz .LBB0_891

; __device__ __forceinline__ u32x2 pk4(f32x4 v) { u32x2 r; r.x = pk2(v.x, v.y); r.y = pk2(v.z, v.w); return r; }
; template <int WHICH, int NRW>
; __device__ __forceinline__ void ln_rows(const Params& p, const int row0, const int lane, const f32x4 (&gv)[4], const f32x4 (&bv)[4]) {
;     ...
;   float s[NRW], s2[NRW];
; #pragma unroll
;   for (int h = 0; h < NRW; ++h) { s[h] = 0.f;
; #pragma unroll
;     for (int j = 0; j < 4; ++j) s[h] += (v[h][j].x + v[h][j].y) + (v[h][j].z + v[h][j].w); }
; #pragma unroll
;   for (int o = 1; o < 64; o <<= 1) {
; #pragma unroll
;     for (int h = 0; h < NRW; ++h) s[h] += __shfl_xor(s[h], o);
;   }
; #pragma unroll
;   for (int h = 0; h < NRW; ++h) { const float mean = s[h] * (1.f / DM); s2[h] = 0.f;
; #pragma unroll
;     for (int j = 0; j < 4; ++j) { v[h][j] = v[h][j] - mean; s2[h] += (v[h][j].x * v[h][j].x + v[h][j].y * v[h][j].y) + (v[h][j].z * v[h][j].z + v[h][j].w * v[h][j].w); } }
; #pragma unroll
;   for (int o = 1; o < 64; o <<= 1) {
; #pragma unroll
;     for (int h = 0; h < NRW; ++h) s2[h] += __shfl_xor(s2[h], o);
;   }
; #pragma unroll
;   for (int h = 0; h < NRW; ++h) {
;     const int row = row0 + h;
;     const float rstd = rsqrtf(s2[h] * (1.f / DM) + LN_EPS_F);
; #pragma unroll
;     for (int j = 0; j < 4; ++j) {
;       const f32x4 o = v[h][j] * rstd * gv[j] + bv[j];
;       if (WHICH == 1) *(u32x2*)(X1b + (size_t)row * DM + j * 256 + lane * 4) = pk4(o);
;       else *(f32x4*)(p.out + (size_t)row * DM + j * 256 + lane * 4) = o;
;     }
;   }
.LBB0_894:
	s_or_b64 exec, exec, s[6:7]
	v_pk_add_f32 v[70:71], v[60:61], v[56:57]
	v_add_f32_e32 v45, v48, v49
	v_add_f32_e32 v43, v70, v71
	v_pk_add_f32 v[70:71], v[58:59], v[54:55]
	v_add_f32_e32 v51, 0, v43
	v_pk_add_f32 v[70:71], v[70:71], v[70:71] op_sel_hi:[0,1]
	v_add_f32_e32 v53, v46, v47
	v_mov_b32_e32 v43, v71
	v_pk_add_f32 v[72:73], v[44:45], v[52:53]
	v_pk_add_f32 v[70:71], v[42:43], v[50:51]
	v_add_u32_e32 v34, s66, v34
	v_pk_add_f32 v[70:71], v[72:73], v[70:71]
	s_nop 0
	v_add_f32_e32 v43, v70, v71
	ds_bpermute_b32 v45, v62, v43
	s_waitcnt lgkmcnt(0)
	v_add_f32_e32 v43, v43, v45
	ds_bpermute_b32 v45, v63, v43
	s_waitcnt lgkmcnt(0)
	v_add_f32_e32 v43, v43, v45
	ds_bpermute_b32 v45, v64, v43
	s_waitcnt lgkmcnt(0)
	v_add_f32_e32 v43, v43, v45
	ds_bpermute_b32 v45, v65, v43
	s_waitcnt lgkmcnt(0)
	v_add_f32_e32 v43, v43, v45
	ds_bpermute_b32 v45, v66, v43
	s_waitcnt lgkmcnt(0)
	v_add_f32_e32 v43, v43, v45
	ds_bpermute_b32 v45, v67, v43
	s_waitcnt lgkmcnt(0)
	v_add_f32_e32 v43, v43, v45
	v_fmac_f32_e32 v60, 0xba800000, v43
	v_fmac_f32_e32 v57, 0xba800000, v43
	v_fmac_f32_e32 v61, 0xba800000, v43
	v_fmac_f32_e32 v58, 0xba800000, v43
	v_fmac_f32_e32 v55, 0xba800000, v43
	v_fmac_f32_e32 v59, 0xba800000, v43
	v_fmac_f32_e32 v56, 0xba800000, v43
	v_fmac_f32_e32 v54, 0xba800000, v43
	v_mov_b32_e32 v70, v61
	v_mov_b32_e32 v71, v57
	v_mov_b32_e32 v57, v60
	v_mov_b32_e32 v60, v59
	v_mov_b32_e32 v61, v55
	v_mov_b32_e32 v55, v58
	v_pk_mul_f32 v[58:59], v[70:71], v[70:71]
	v_pk_mul_f32 v[72:73], v[56:57], v[56:57]
	v_pk_mul_f32 v[74:75], v[60:61], v[60:61]
	v_pk_mul_f32 v[76:77], v[54:55], v[54:55]
	v_pk_mov_b32 v[78:79], v[72:73], v[58:59] op_sel:[1,0]
	v_mov_b32_e32 v73, v59
	v_pk_mov_b32 v[58:59], v[76:77], v[74:75] op_sel:[1,0]
	v_mov_b32_e32 v77, v75
	v_pk_add_f32 v[58:59], v[58:59], v[76:77]
	v_fmac_f32_e32 v48, 0xba800000, v43
	v_pk_add_f32 v[58:59], v[58:59], v[58:59] op_sel_hi:[0,1]
	v_fmac_f32_e32 v49, 0xba800000, v43
	v_fmac_f32_e32 v46, 0xba800000, v43
	v_mul_f32_e32 v58, v48, v48
	v_pk_add_f32 v[72:73], v[78:79], v[72:73]
	v_fmac_f32_e32 v47, 0xba800000, v43
	v_pk_fma_f32 v[74:75], v[48:49], v[48:49], v[58:59] op_sel_hi:[1,1,0]
	v_mul_f32_e32 v58, v46, v46
	v_pk_add_f32 v[72:73], v[72:73], v[72:73] op_sel_hi:[0,1]
	v_pk_fma_f32 v[76:77], v[46:47], v[46:47], v[58:59] op_sel_hi:[1,1,0]
	v_fmac_f32_e32 v50, 0xba800000, v43
	v_fmac_f32_e32 v42, 0xba800000, v43
	v_fmac_f32_e32 v52, 0xba800000, v43
	v_fmac_f32_e32 v44, 0xba800000, v43
	v_mul_f32_e32 v74, v44, v44
	v_mul_f32_e32 v76, v52, v52
	v_mul_f32_e32 v72, v42, v42
	v_mul_f32_e32 v58, v50, v50
	v_pk_add_f32 v[74:75], v[74:75], v[76:77]
	v_pk_add_f32 v[58:59], v[72:73], v[58:59]
	s_nop 0
	v_pk_add_f32 v[58:59], v[74:75], v[58:59]
	s_nop 0
	v_add_f32_e32 v43, v58, v59
	ds_bpermute_b32 v45, v62, v43
	v_add_co_u32_e64 v58, s[6:7], s16, v40
	s_waitcnt lgkmcnt(0)
	v_add_f32_e32 v43, v43, v45
	ds_bpermute_b32 v45, v63, v43
	v_addc_co_u32_e64 v59, s[6:7], 0, v41, s[6:7]
	v_lshl_add_u64 v[40:41], v[40:41], 0, s[10:11]
	s_waitcnt lgkmcnt(0)
	v_add_f32_e32 v43, v43, v45
	ds_bpermute_b32 v45, v64, v43
	s_waitcnt lgkmcnt(0)
	v_add_f32_e32 v43, v43, v45
	ds_bpermute_b32 v45, v65, v43
	s_waitcnt lgkmcnt(0)
	v_add_f32_e32 v43, v43, v45
	ds_bpermute_b32 v45, v66, v43
	s_waitcnt lgkmcnt(0)
	v_add_f32_e32 v43, v43, v45
	ds_bpermute_b32 v45, v67, v43
	s_waitcnt lgkmcnt(0)
	v_add_f32_e32 v43, v43, v45
	v_fmamk_f32 v43, v43, 0x3a800000, v68
	v_mul_f32_e32 v45, 0x4b800000, v43
	v_cmp_gt_f32_e32 vcc, s15, v43
	s_nop 1
	v_cndmask_b32_e32 v43, v43, v45, vcc
	v_rsq_f32_e32 v43, v43
	s_nop 0
	v_mul_f32_e32 v45, 0x45800000, v43
	v_cndmask_b32_e32 v72, v43, v45, vcc
	v_pk_mul_f32 v[56:57], v[56:57], v[72:73] op_sel_hi:[1,0]
	v_pk_mul_f32 v[70:71], v[70:71], v[72:73] op_sel_hi:[1,0]
	v_mov_b32_e32 v45, v52
	v_mov_b32_e32 v43, v50
	s_waitcnt vmcnt(6)
	v_pk_fma_f32 v[70:71], v[4:5], v[70:71], v[8:9]
	v_pk_fma_f32 v[56:57], v[2:3], v[56:57], v[6:7]
	v_pk_mul_f32 v[44:45], v[44:45], v[72:73] op_sel_hi:[1,0]
	v_pk_mul_f32 v[42:43], v[42:43], v[72:73] op_sel_hi:[1,0]
	v_cvt_pk_bf16_f32 v56, v56, v57
	v_cvt_pk_bf16_f32 v57, v70, v71
	s_waitcnt vmcnt(0)
	v_pk_fma_f32 v[42:43], v[28:29], v[42:43], v[32:33]
	v_pk_fma_f32 v[44:45], v[26:27], v[44:45], v[30:31]
	v_pk_mul_f32 v[54:55], v[54:55], v[72:73] op_sel_hi:[1,0]
	global_store_dwordx2 v[58:59], v[56:57], off sc1
	v_pk_mul_f32 v[56:57], v[60:61], v[72:73] op_sel_hi:[1,0]
	v_pk_mul_f32 v[48:49], v[48:49], v[72:73] op_sel_hi:[1,0]
	v_pk_mul_f32 v[46:47], v[46:47], v[72:73] op_sel_hi:[1,0]
	v_cvt_pk_bf16_f32 v44, v44, v45
	v_cvt_pk_bf16_f32 v45, v42, v43
	v_add_u32_e32 v42, 0x4000, v34
	v_pk_fma_f32 v[56:57], v[12:13], v[56:57], v[16:17]
	v_pk_fma_f32 v[54:55], v[10:11], v[54:55], v[14:15]
	v_pk_fma_f32 v[46:47], v[20:21], v[46:47], v[24:25]
	v_pk_fma_f32 v[48:49], v[18:19], v[48:49], v[22:23]
	v_cmp_lt_i32_e32 vcc, s17, v42
	v_cvt_pk_bf16_f32 v54, v54, v55
	v_cvt_pk_bf16_f32 v55, v56, v57
	v_cvt_pk_bf16_f32 v48, v48, v49
	v_cvt_pk_bf16_f32 v49, v46, v47
	s_or_b64 s[12:13], vcc, s[12:13]
	global_store_dwordx2 v[58:59], v[54:55], off offset:512 sc1
	global_store_dwordx2 v[58:59], v[48:49], off offset:1024 sc1
	global_store_dwordx2 v[58:59], v[44:45], off offset:1536 sc1
	s_andn2_b64 exec, exec, s[12:13]
	s_cbranch_execz .LBB0_899

; __device__ __forceinline__ unsigned xb_ld(unsigned* p)              { return __hip_atomic_load(p, __ATOMIC_RELAXED, __HIP_MEMORY_SCOPE_AGENT); }
; __device__ __forceinline__ unsigned xb_add(unsigned* p, unsigned v) { return __hip_atomic_fetch_add(p, v, __ATOMIC_RELAXED, __HIP_MEMORY_SCOPE_AGENT); }
; #define XB_SPIN(cond, bar) do { unsigned _sp = 0; while (cond) { __builtin_amdgcn_s_sleep(1); \
;     if ((++_sp & 255u) == 0u) { if (xb_ld(&(bar)[XB_TMO])) break; if (_sp > XB_SPIN_CAP) { atomicAdd(&(bar)[XB_TMO], 1u); break; } } } } while (0)
; __device__ __forceinline__ void xcd_barrier(const XcdBarrier& b) {
;     asm volatile("s_waitcnt vmcnt(0)" ::: "memory");
;     __syncthreads();
;     if (threadIdx.x == 0) {
;         unsigned* bar = b.bar;
;         __builtin_amdgcn_s_waitcnt(0);
;         unsigned nloc = b.st[0], nx = b.st[1];
;         if (nloc == 0u) { xcd_barrier_complete(bar, b.x, nloc, nx); b.st[0] = nloc; b.st[1] = nx; }
;         const unsigned old = xb_add(&bar[XB_XSUB(b.x)], 1u);
;         const unsigned gen = old / nloc;
;         if (old + 1u == (gen + 1u) * nloc) {
;             __builtin_amdgcn_fence(__ATOMIC_RELEASE, "agent");
;             asm volatile("s_waitcnt vmcnt(0)" ::: "memory");
;             const unsigned og = xb_add(&bar[XB_TOP], 1u);
;             const unsigned tg = og / nx;
;             if (og + 1u == (tg + 1u) * nx) xb_add(&bar[XB_TOPGEN], 1u);
;             else XB_SPIN(xb_ld(&bar[XB_TOPGEN]) == tg, bar);
;             __builtin_amdgcn_fence(__ATOMIC_ACQUIRE, "agent");
;             xb_add(&bar[XB_XGEN(b.x)], 1u);
;             asm volatile("s_waitcnt vmcnt(0)" ::: "memory");
.LBB0_915:
	v_mov_b32_e32 v4, 0x20000
	ds_read2_b32 v[2:3], v4 offset1:1
	v_readlane_b32 s3, v244, 30
	s_nop 0
	s_lshl_b32 s3, s3, 8
	s_getpc_b64 s[8:9]
	s_add_u32 s8, s8, g_xbar@rel32@lo+4
	s_addc_u32 s9, s9, g_xbar@rel32@hi+12
	s_add_u32 s8, s8, s3
	s_addc_u32 s9, s9, 0
	v_mov_b32_e32 v5, 0x1000
	v_mov_b32_e32 v6, 1
	global_atomic_add v5, v5, v6, s[8:9] offset:1024 sc0
	s_movk_i32 s3, 7
	s_waitcnt lgkmcnt(0)
	v_mul_lo_u32 v2, v2, s3
	v_mul_lo_u32 v3, v3, s3
	s_waitcnt vmcnt(0)
	v_add_u32_e32 v5, 1, v5
	v_cmp_ne_u32_e32 vcc, v5, v2
	s_getpc_b64 s[8:9]
	s_add_u32 s8, s8, g_xbar@rel32@lo+13316
	s_addc_u32 s9, s9, g_xbar@rel32@hi+13324
	v_mov_b32_e32 v4, 0
	s_cbranch_vccnz .Lfb6_spin0
	s_nop 0
	s_waitcnt vmcnt(0) lgkmcnt(0)
	global_atomic_add v4, v6, s[8:9]

; __device__ __forceinline__ float gelu_tanh(float x) { float z = 1.5957691216057308f * (x + 0.044715f * x * x * x); return x * rcp_nr(1.f + __expf(fminf(-z, 80.f))); }
; __device__ __forceinline__ u32x2 pk4(f32x4 v) { u32x2 r; r.x = pk2(v.x, v.y); r.y = pk2(v.z, v.w); return r; }
; __device__ __forceinline__ void fixup_phase(const Params& p) {
;     ...
;     const f32x4 a0 = *(const f32x4*)(HA0 + ((size_t)rb * 2 + rl) * DFF + j0);
;     const f32x4 g = *(const f32x4*)(HG0 + ((size_t)rb * 2 + rl) * DFF + j0);
;     const f32x4 pm1 = *(const f32x4*)(HA1 + ((size_t)(rb - 1) * 2 + 1) * DFF + j0);
;     const f32x4 pm2 = *(const f32x4*)(HA1 + ((size_t)(rb - 1) * 2 + 0) * DFF + j0);
;     f32x4 am1, am2;
;     if (rl == 0) { am1 = pm1; am2 = pm2; }
;     else { am1 = *(const f32x4*)(HA0 + ((size_t)rb * 2 + 0) * DFF + j0); am2 = pm1; }
;     const f32x4 w0 = *(const f32x4*)(p.in[23] + j0), w1 = *(const f32x4*)(p.in[23] + DFF + j0), w2 = *(const f32x4*)(p.in[23] + 2 * DFF + j0);
;     const f32x4 cb = *(const f32x4*)(p.in[24] + j0);
;     f32x4 h;
;     h.x = gelu_tanh(cb.x + w0.x * am2.x + w1.x * am1.x + w2.x * a0.x) * g.x;
;     h.y = gelu_tanh(cb.y + w0.y * am2.y + w1.y * am1.y + w2.y * a0.y) * g.y;
;     h.z = gelu_tanh(cb.z + w0.z * am2.z + w1.z * am1.z + w2.z * a0.z) * g.z;
;     h.w = gelu_tanh(cb.w + w0.w * am2.w + w1.w * am1.w + w2.w * a0.w) * g.w;
;     *(u32x2*)(H + ((size_t)rb * 64 + rl) * DFF + j0) = pk4(h);
.LBB0_1157:
	s_or_b64 exec, exec, s[26:27]
	v_readlane_b32 s36, v244, 35
	v_readlane_b32 s37, v244, 36
	v_readlane_b32 s38, v244, 37
	v_readlane_b32 s39, v244, 38
	v_readlane_b32 s40, v244, 39
	v_readlane_b32 s41, v244, 40
	v_readlane_b32 s42, v244, 41
	v_readlane_b32 s43, v244, 42
	v_readlane_b32 s36, v244, 4
	v_readlane_b32 s50, v244, 49
	v_readlane_b32 s51, v244, 50
	v_readlane_b32 s37, v244, 5
	v_readlane_b32 s38, v244, 6
	v_lshl_add_u64 v[18:19], s[50:51], 0, v[24:25]
	v_lshl_add_u64 v[26:27], s[36:37], 0, v[24:25]
	global_load_dwordx4 v[18:21], v[18:19], off
	v_readlane_b32 s39, v244, 7
	global_load_dwordx4 v[30:33], v[26:27], off
	v_lshl_add_u64 v[26:27], s[14:15], 0, v[24:25]
	global_load_dwordx4 v[34:37], v[26:27], off
	v_lshl_add_u64 v[24:25], s[16:17], 0, v[24:25]
	global_load_dwordx4 v[24:27], v[24:25], off
	v_readlane_b32 s36, v244, 0
	v_readlane_b32 s38, v244, 2
	v_readlane_b32 s39, v244, 3
	v_readlane_b32 s44, v244, 43
	v_readlane_b32 s45, v244, 44
	v_readlane_b32 s46, v244, 45
	v_readlane_b32 s47, v244, 46
	v_readlane_b32 s48, v244, 47
	v_readlane_b32 s49, v244, 48
	v_readlane_b32 s40, v244, 8
	v_readlane_b32 s41, v244, 9
	v_readlane_b32 s42, v244, 10
	v_readlane_b32 s43, v244, 11
	v_readlane_b32 s37, v244, 1
	s_waitcnt vmcnt(2)
	v_pk_fma_f32 v[16:17], v[16:17], v[20:21], v[32:33]
	v_pk_fma_f32 v[14:15], v[14:15], v[18:19], v[30:31]
	s_waitcnt vmcnt(1)
	v_pk_fma_f32 v[12:13], v[12:13], v[36:37], v[16:17]
	v_pk_fma_f32 v[10:11], v[10:11], v[34:35], v[14:15]
	s_waitcnt vmcnt(0)
	v_pk_fma_f32 v[8:9], v[8:9], v[26:27], v[12:13]
	v_pk_fma_f32 v[6:7], v[6:7], v[24:25], v[10:11]
	v_mul_f32_e32 v12, 0x3d372713, v8
	v_mul_f32_e32 v10, 0x3d372713, v6
	v_mul_f32_e32 v11, 0x3d372713, v7
	v_mul_f32_e32 v13, 0x3d372713, v9
	v_mul_f32_e32 v10, v6, v10
	v_mul_f32_e32 v11, v7, v11
	v_mul_f32_e32 v12, v8, v12
	v_mul_f32_e32 v13, v9, v13
	v_fma_f32 v10, v6, v10, v6
	v_fma_f32 v11, v7, v11, v7
	v_fma_f32 v12, v8, v12, v8
	v_fma_f32 v13, v9, v13, v9
	v_mul_f32_e32 v10, 0xbfcc422a, v10
	v_mul_f32_e32 v11, 0xbfcc422a, v11
	v_mul_f32_e32 v12, 0xbfcc422a, v12
	v_mul_f32_e32 v13, 0xbfcc422a, v13
	v_min_f32_e32 v10, 0x42a00000, v10
	v_min_f32_e32 v11, 0x42a00000, v11
	v_min_f32_e32 v12, 0x42a00000, v12
	v_min_f32_e32 v13, 0x42a00000, v13
	v_mul_f32_e32 v10, 0x3fb8aa3b, v10
	v_mul_f32_e32 v11, 0x3fb8aa3b, v11
	v_mul_f32_e32 v12, 0x3fb8aa3b, v12
	v_mul_f32_e32 v13, 0x3fb8aa3b, v13
	v_exp_f32_e32 v10, v10
	v_exp_f32_e32 v11, v11
	v_exp_f32_e32 v12, v12
	v_exp_f32_e32 v13, v13
	v_lshl_or_b32 v20, v28, 6, v29
	v_pk_add_f32 v[10:11], v[10:11], 1.0 op_sel_hi:[1,0]
	v_mov_b64_e32 v[14:15], s[38:39]
	v_pk_add_f32 v[12:13], v[12:13], 1.0 op_sel_hi:[1,0]
	v_rcp_f32_e32 v16, v10
	v_rcp_f32_e32 v17, v11
	v_rcp_f32_e32 v18, v12
	v_rcp_f32_e32 v19, v13
	v_mad_i64_i32 v[14:15], s[26:27], v20, s29, v[14:15]
	v_pk_fma_f32 v[10:11], v[10:11], v[16:17], 1.0 op_sel_hi:[1,1,0] neg_lo:[1,0,0] neg_hi:[1,0,0]
	v_pk_fma_f32 v[12:13], v[12:13], v[18:19], 1.0 op_sel_hi:[1,1,0] neg_lo:[1,0,0] neg_hi:[1,0,0]
	v_pk_fma_f32 v[10:11], v[16:17], v[10:11], v[16:17]
	v_pk_fma_f32 v[12:13], v[18:19], v[12:13], v[18:19]
	v_pk_mul_f32 v[6:7], v[6:7], v[10:11]
	v_pk_mul_f32 v[8:9], v[8:9], v[12:13]
	v_pk_mul_f32 v[2:3], v[2:3], v[6:7]
	v_pk_mul_f32 v[4:5], v[4:5], v[8:9]
	v_cvt_pk_bf16_f32 v2, v2, v3
	v_cvt_pk_bf16_f32 v3, v4, v5
	v_lshl_add_u64 v[4:5], v[22:23], 1, v[14:15]
	global_store_dwordx2 v[4:5], v[2:3], off sc1

; __device__ __forceinline__ unsigned xb_ld(unsigned* p)              { return __hip_atomic_load(p, __ATOMIC_RELAXED, __HIP_MEMORY_SCOPE_AGENT); }
; __device__ __forceinline__ unsigned xb_add(unsigned* p, unsigned v) { return __hip_atomic_fetch_add(p, v, __ATOMIC_RELAXED, __HIP_MEMORY_SCOPE_AGENT); }
; #define XB_SPIN(cond, bar) do { unsigned _sp = 0; while (cond) { __builtin_amdgcn_s_sleep(1); \
;     if ((++_sp & 255u) == 0u) { if (xb_ld(&(bar)[XB_TMO])) break; if (_sp > XB_SPIN_CAP) { atomicAdd(&(bar)[XB_TMO], 1u); break; } } } } while (0)
; __device__ __forceinline__ void xcd_barrier(const XcdBarrier& b) {
;     asm volatile("s_waitcnt vmcnt(0)" ::: "memory");
;     __syncthreads();
;     if (threadIdx.x == 0) {
;         unsigned* bar = b.bar;
;         __builtin_amdgcn_s_waitcnt(0);
;         unsigned nloc = b.st[0], nx = b.st[1];
;         if (nloc == 0u) { xcd_barrier_complete(bar, b.x, nloc, nx); b.st[0] = nloc; b.st[1] = nx; }
;         const unsigned old = xb_add(&bar[XB_XSUB(b.x)], 1u);
;         const unsigned gen = old / nloc;
;         if (old + 1u == (gen + 1u) * nloc) {
;             __builtin_amdgcn_fence(__ATOMIC_RELEASE, "agent");
;             asm volatile("s_waitcnt vmcnt(0)" ::: "memory");
;             const unsigned og = xb_add(&bar[XB_TOP], 1u);
;             const unsigned tg = og / nx;
;             if (og + 1u == (tg + 1u) * nx) xb_add(&bar[XB_TOPGEN], 1u);
;             else XB_SPIN(xb_ld(&bar[XB_TOPGEN]) == tg, bar);
;             __builtin_amdgcn_fence(__ATOMIC_ACQUIRE, "agent");
;             xb_add(&bar[XB_XGEN(b.x)], 1u);
;             asm volatile("s_waitcnt vmcnt(0)" ::: "memory");
.LBB0_1180:
	v_mov_b32_e32 v1, 0x20000
	ds_read2_b32 v[2:3], v1 offset1:1
	v_readlane_b32 s8, v244, 30
	s_nop 0
	s_lshl_b32 s8, s8, 8
	s_getpc_b64 s[6:7]
	s_add_u32 s6, s6, g_xbar@rel32@lo+4
	s_addc_u32 s7, s7, g_xbar@rel32@hi+12
	s_add_u32 s6, s6, s8
	s_addc_u32 s7, s7, 0
	v_mov_b32_e32 v4, 0x1000
	v_mov_b32_e32 v5, 1
	global_atomic_add v4, v4, v5, s[6:7] offset:1024 sc0
	s_movk_i32 s8, 9
	s_waitcnt lgkmcnt(0)
	v_mul_lo_u32 v2, v2, s8
	v_mul_lo_u32 v3, v3, s8
	s_waitcnt vmcnt(0)
	v_add_u32_e32 v4, 1, v4
	v_cmp_ne_u32_e32 vcc, v4, v2
	s_getpc_b64 s[6:7]
	s_add_u32 s6, s6, g_xbar@rel32@lo+13316
	s_addc_u32 s7, s7, g_xbar@rel32@hi+13324
	v_mov_b32_e32 v1, 0
	s_cbranch_vccnz .Lfb8_spin0
	s_nop 0
	s_waitcnt vmcnt(0) lgkmcnt(0)
	global_atomic_add v1, v5, s[6:7]
